# NSA tile loop: V and K fragment LDS reads hoisted (V before the exp block, K to the iteration top) into dead VGPRs; QK/PV MFMAs back to back
# baseline (speedup 1.0000x reference)
; #define LAS __attribute__((address_space(3)))
; DI void nsa_attn_phase(int wv, LAS unsigned char* lds, const bf16_t* Q, const bf16_t* slab, const bf16_t* VT2, const float* gates, const bf16_t* KCMP, const bf16_t* VCMPT,
;                        const float* rel_bias, bf16_t* O) {
;     ...
;                 auto lstore = [&](int buf) {
;                     LAS unsigned char* kb = lds + OFF_BUF + buf * TILE;
;                     *(LAS u32x4*)(kb + (tid >> 3) * KS + (tid & 7) * 16) = rk;
;                     lds_store16_as2x8(kb + VOFF + (tid >> 3) * VS + (tid & 7) * 16, rv);
;                 };
;     ...
;                 for (;;) {
;                     const int bn = bi == 2 ? 0 : bi + 1;
;                     if (jn >= 0) lstore(bn);
;                     int jnn = -1; if (tiles) { jnn = __builtin_ctz(tiles); tiles &= tiles - 1; gload(jnn); }
.LBB0_2421:
	s_mul_i32 s70, s0, 0x4600
	v_add3_u32 v18, s70, v212, v241
	ds_read_b128 v[52:55], v18 offset:35328
	ds_read_b128 v[56:59], v18 offset:35360
	ds_read_b128 v[60:63], v18 offset:35392
	ds_read_b128 v[64:67], v18 offset:35424
	ds_read_b128 v[68:71], v18 offset:39936
	ds_read_b128 v[72:75], v18 offset:39968
	ds_read_b128 v[76:79], v18 offset:40000
	ds_read_b128 v[224:227], v18 offset:40032
	s_add_i32 s1, s0, 1
	s_cmp_lg_u32 s0, 2
	s_cselect_b32 s96, s1, 0
	v_cmp_lt_i32_e32 vcc, -1, v244
	s_and_saveexec_b64 s[4:5], vcc
	s_cbranch_execz .LBB0_2423
	s_mul_i32 s1, s96, 0x4600
	s_add_i32 s1, s1, 0
	v_add3_u32 v0, s1, v236, v238
	v_add_u32_e32 v2, s1, v239
	v_add3_u32 v2, v2, v238, s62
	s_waitcnt vmcnt(0)
	ds_write_b128 v0, v[196:199] offset:35328
	ds_write2_b64 v2, v[200:201], v[202:203] offset1:1

; #define LAS __attribute__((address_space(3)))
; DI f32x16 mfma32(bf16x8 a, bf16x8 b, f32x16 c) { return __builtin_amdgcn_mfma_f32_32x32x16_bf16(a, b, c, 0, 0, 0); }
; DI f32x16 zero16() { f32x16 z; for (int i = 0; i < 16; ++i) z[i] = 0.f; return z; }
; template <int NKS>
; DI void qk_tile(const LAS unsigned char* kt, int kstride, const bf16x8 (&qf)[NKS], f32x16 (&s)[2], int r, int hh, const bf16x8 rf) {
;     const bf16x8 of = ones_frag(hh);
; #pragma unroll
;     for (int t = 0; t < 2; ++t) {
;         bf16x8 kf[NKS];
; #pragma unroll
;         for (int ks = 0; ks < NKS; ++ks) kf[ks] = *(const LAS bf16x8*)(kt + (32 * t + r) * kstride + 32 * ks + 16 * hh);
;         __builtin_amdgcn_sched_barrier(0);
;         s[t] = zero16();
; #pragma unroll
;         for (int ks = 0; ks < NKS; ++ks) s[t] = mfma32(kf[ks], qf[ks], s[t]);
;         s[t] = mfma32(of, rf, s[t]);
;     }
; DI void nsa_attn_phase(int wv, LAS unsigned char* lds, const bf16_t* Q, const bf16_t* slab, const bf16_t* VT2, const float* gates, const bf16_t* KCMP, const bf16_t* VCMPT,
;                        const float* rel_bias, bf16_t* O) {
;     ...
;                 auto process = [&](const LAS unsigned char* kb, int j) {
;                     const int k0 = 64 * j;
;                     const bool selbit = (br == 0) ? (((mysel >> j) & 1u) != 0u) : true;
;                     if (br == 0 && __ballot(selbit) == 0ull) return;
;                     const bool far = (TW - (k0 + 63) >= 127) && (br == 0 || (TW + 31 - k0 < 512));
;                     f32x16 s[2];
;                     qk_tile<4>(kb, KS, qf, s, r, hh, ref_frag(-m, far ? (selbit ? c31 : NEGF) : 0.f, hh));
;                     if (!far) {
;                         const int d0 = tq - k0 - 4 * hh;
; #pragma unroll
;                         for (int t = 0; t < 2; ++t)
; #pragma unroll
;                             for (int i = 0; i < 16; ++i) {
;                                 const int dist = d0 - (32 * t + (i & 3) + 8 * (i >> 2));
;                                 const float bias = mylut[dist < 0 ? 0 : (dist > 127 ? 127 : dist)];
;                                 const bool valid = selbit && dist >= 0 && (br == 0 || dist < 512);
;                                 s[t][i] = valid ? s[t][i] + bias : NEGF;
;                             }
.LBB0_2427:
	s_andn2_b64 vcc, exec, s[6:7]
	s_cbranch_vccnz .LBB0_2420
	s_mulk_i32 s0, 0x4600
	s_add_i32 s0, s0, 0
	v_cvt_pk_bf16_f32 v3, -v4, s0
	v_perm_b32 v3, 0, v3, v229
	v_lshlrev_b32_e32 v7, 16, v3
	v_sub_f32_e64 v7, -v4, v7
	v_cvt_pk_bf16_f32 v7, v7, s0
	v_mul_i32_i24_e32 v0, 0xffffffc0, v144
	v_lshl_or_b32 v3, v7, 16, v3
	v_add_u32_e32 v2, s92, v0
	s_movk_i32 s1, 0x7e
	v_cmp_lt_i32_e64 s[6:7], s1, v2
	v_add_u32_e32 v2, s93, v0
	v_cmp_gt_i32_e32 vcc, s83, v2
	s_or_b64 s[30:31], s[8:9], vcc
	s_or_b64 vcc, s[26:27], s[4:5]
	v_mov_b32_e32 v2, 0xfffff14a
	v_cndmask_b32_e32 v2, v2, v240, vcc
	s_and_b64 s[4:5], s[6:7], s[30:31]
	v_cndmask_b32_e64 v2, 0, v2, s[4:5]
	v_mov_b32_e32 v208, 0x1100
	v_perm_b32 v2, 0, v2, v229
	s_xor_b64 s[4:5], s[4:5], -1
	v_cndmask_b32_e64 v246, 0, v3, s[2:3]
	v_cndmask_b32_e64 v247, 0, v2, s[2:3]
	v_mov_b32_e32 v248, v1
	v_mov_b32_e32 v249, v1
	s_waitcnt lgkmcnt(0)
	v_mfma_f32_32x32x16_bf16 v[160:175], v[52:55], v[176:179], 0
	v_mfma_f32_32x32x16_bf16 v[160:175], v[56:59], v[180:183], v[160:175]
	v_mfma_f32_32x32x16_bf16 v[160:175], v[60:63], v[184:187], v[160:175]
	v_mfma_f32_32x32x16_bf16 v[160:175], v[64:67], v[188:191], v[160:175]
	v_mfma_f32_32x32x16_bf16 v[160:175], v[192:195], v[246:249], v[160:175]
	v_mfma_f32_32x32x16_bf16 v[144:159], v[68:71], v[176:179], 0
	v_mfma_f32_32x32x16_bf16 v[144:159], v[72:75], v[180:183], v[144:159]
	v_mfma_f32_32x32x16_bf16 v[144:159], v[76:79], v[184:187], v[144:159]
	v_mfma_f32_32x32x16_bf16 v[144:159], v[224:227], v[188:191], v[144:159]
	v_mfma_f32_32x32x16_bf16 v[144:159], v[192:195], v[246:249], v[144:159]
	s_and_saveexec_b64 s[6:7], s[4:5]
	s_cbranch_execz .LBB0_2430
	v_add_u32_e32 v2, v0, v210
	v_sub_u32_e32 v3, v2, v233
	v_or_b32_e32 v0, 8, v233
	v_sub_u32_e32 v0, v2, v0
	v_or_b32_e32 v7, 16, v233
	v_sub_u32_e32 v7, v2, v7
	v_or_b32_e32 v246, 24, v233
	v_sub_u32_e32 v2, v2, v246
	v_med3_i32 v8, v3, 0, v230
	v_lshl_add_u32 v8, v8, 2, s57
	ds_read_b32 v8, v8
	v_subrev_u32_e32 v9, 1, v3
	v_med3_i32 v9, v9, 0, v230
	v_lshl_add_u32 v9, v9, 2, s57
	ds_read_b32 v9, v9
	v_subrev_u32_e32 v10, 2, v3
	v_med3_i32 v10, v10, 0, v230
	v_lshl_add_u32 v10, v10, 2, s57
	ds_read_b32 v10, v10
	v_subrev_u32_e32 v11, 3, v3
	v_med3_i32 v11, v11, 0, v230
	v_lshl_add_u32 v11, v11, 2, s57
	ds_read_b32 v11, v11
	v_med3_i32 v12, v0, 0, v230
	v_lshl_add_u32 v12, v12, 2, s57
	ds_read_b32 v12, v12
	v_subrev_u32_e32 v13, 1, v0
	v_med3_i32 v13, v13, 0, v230
	v_lshl_add_u32 v13, v13, 2, s57
	ds_read_b32 v13, v13
	v_subrev_u32_e32 v14, 2, v0
	v_med3_i32 v14, v14, 0, v230
	v_lshl_add_u32 v14, v14, 2, s57
	ds_read_b32 v14, v14
	v_subrev_u32_e32 v15, 3, v0
	v_med3_i32 v15, v15, 0, v230
	v_lshl_add_u32 v15, v15, 2, s57
	ds_read_b32 v15, v15
	v_med3_i32 v224, v7, 0, v230
	v_lshl_add_u32 v224, v224, 2, s57
	ds_read_b32 v224, v224
	v_subrev_u32_e32 v225, 1, v7
	v_med3_i32 v225, v225, 0, v230
	v_lshl_add_u32 v225, v225, 2, s57
	ds_read_b32 v225, v225
	v_subrev_u32_e32 v226, 2, v7
	v_med3_i32 v226, v226, 0, v230
	v_lshl_add_u32 v226, v226, 2, s57
	ds_read_b32 v226, v226
	v_subrev_u32_e32 v227, 3, v7
	v_med3_i32 v227, v227, 0, v230
	v_lshl_add_u32 v227, v227, 2, s57
	ds_read_b32 v227, v227
	v_med3_i32 v250, v2, 0, v230
	v_lshl_add_u32 v250, v250, 2, s57
	ds_read_b32 v250, v250
	v_subrev_u32_e32 v251, 1, v2
	v_med3_i32 v251, v251, 0, v230
	v_lshl_add_u32 v251, v251, 2, s57
	ds_read_b32 v251, v251
	v_subrev_u32_e32 v252, 2, v2
	v_med3_i32 v252, v252, 0, v230
	v_lshl_add_u32 v252, v252, 2, s57
	ds_read_b32 v252, v252
	v_subrev_u32_e32 v253, 3, v2
	v_med3_i32 v253, v253, 0, v230
	v_lshl_add_u32 v253, v253, 2, s57
	ds_read_b32 v253, v253
	v_cmp_lt_i32_e64 s[4:5], -1, v3
	s_and_b64 s[30:31], vcc, s[4:5]
	v_cmp_gt_u32_e64 s[4:5], s83, v3
	s_or_b64 s[4:5], s[8:9], s[4:5]
	s_waitcnt lgkmcnt(15)
	v_add_f32_e32 v8, v160, v8
	s_and_b64 s[4:5], s[30:31], s[4:5]
	v_cndmask_b32_e64 v160, v231, v8, s[4:5]
	v_subrev_u32_e32 v247, 1, v3
	v_cmp_lt_i32_e64 s[4:5], -1, v247
	s_and_b64 s[30:31], vcc, s[4:5]
	v_cmp_gt_u32_e64 s[4:5], s83, v247
	s_or_b64 s[4:5], s[8:9], s[4:5]
	s_waitcnt lgkmcnt(14)
	v_add_f32_e32 v9, v161, v9
	s_and_b64 s[4:5], s[30:31], s[4:5]
	v_cndmask_b32_e64 v161, v231, v9, s[4:5]
	v_subrev_u32_e32 v246, 2, v3
	v_cmp_lt_i32_e64 s[4:5], -1, v246
	s_and_b64 s[30:31], vcc, s[4:5]
	v_cmp_gt_u32_e64 s[4:5], s83, v246
	s_or_b64 s[4:5], s[8:9], s[4:5]
	s_waitcnt lgkmcnt(13)
	v_add_f32_e32 v10, v162, v10
	s_and_b64 s[4:5], s[30:31], s[4:5]
	v_cndmask_b32_e64 v162, v231, v10, s[4:5]
	v_subrev_u32_e32 v247, 3, v3
	v_cmp_lt_i32_e64 s[4:5], -1, v247
	s_and_b64 s[30:31], vcc, s[4:5]
	v_cmp_gt_u32_e64 s[4:5], s83, v247
	s_or_b64 s[4:5], s[8:9], s[4:5]
	s_waitcnt lgkmcnt(12)
	v_add_f32_e32 v11, v163, v11
	s_and_b64 s[4:5], s[30:31], s[4:5]
	v_cndmask_b32_e64 v163, v231, v11, s[4:5]
	v_cmp_lt_i32_e64 s[4:5], -1, v0
	s_and_b64 s[30:31], vcc, s[4:5]
	v_cmp_gt_u32_e64 s[4:5], s83, v0
	s_or_b64 s[4:5], s[8:9], s[4:5]
	s_waitcnt lgkmcnt(11)
	v_add_f32_e32 v12, v164, v12
	s_and_b64 s[4:5], s[30:31], s[4:5]
	v_cndmask_b32_e64 v164, v231, v12, s[4:5]
	v_subrev_u32_e32 v247, 1, v0
	v_cmp_lt_i32_e64 s[4:5], -1, v247
	s_and_b64 s[30:31], vcc, s[4:5]
	v_cmp_gt_u32_e64 s[4:5], s83, v247
	s_or_b64 s[4:5], s[8:9], s[4:5]
	s_waitcnt lgkmcnt(10)
	v_add_f32_e32 v13, v165, v13
	s_and_b64 s[4:5], s[30:31], s[4:5]
	v_cndmask_b32_e64 v165, v231, v13, s[4:5]
	v_subrev_u32_e32 v246, 2, v0
	v_cmp_lt_i32_e64 s[4:5], -1, v246
	s_and_b64 s[30:31], vcc, s[4:5]
	v_cmp_gt_u32_e64 s[4:5], s83, v246
	s_or_b64 s[4:5], s[8:9], s[4:5]
	s_waitcnt lgkmcnt(9)
; DI void nsa_attn_phase(int wv, LAS unsigned char* lds, const bf16_t* Q, const bf16_t* slab, const bf16_t* VT2, const float* gates, const bf16_t* KCMP, const bf16_t* VCMPT,
;                        const float* rel_bias, bf16_t* O) {
;     ...
;                     if (!far) {
;                         const int d0 = tq - k0 - 4 * hh;
; #pragma unroll
;                         for (int t = 0; t < 2; ++t)
; #pragma unroll
;                             for (int i = 0; i < 16; ++i) {
;                                 const int dist = d0 - (32 * t + (i & 3) + 8 * (i >> 2));
;                                 const float bias = mylut[dist < 0 ? 0 : (dist > 127 ? 127 : dist)];
;                                 const bool valid = selbit && dist >= 0 && (br == 0 || dist < 512);
;                                 s[t][i] = valid ? s[t][i] + bias : NEGF;
;                             }
	v_add_f32_e32 v14, v166, v14
	s_and_b64 s[4:5], s[30:31], s[4:5]
	v_cndmask_b32_e64 v166, v231, v14, s[4:5]
	v_subrev_u32_e32 v247, 3, v0
	v_cmp_lt_i32_e64 s[4:5], -1, v247
	s_and_b64 s[30:31], vcc, s[4:5]
	v_cmp_gt_u32_e64 s[4:5], s83, v247
	s_or_b64 s[4:5], s[8:9], s[4:5]
	s_waitcnt lgkmcnt(8)
	v_add_f32_e32 v15, v167, v15
	s_and_b64 s[4:5], s[30:31], s[4:5]
	v_cndmask_b32_e64 v167, v231, v15, s[4:5]
	v_subrev_u32_e32 v8, 32, v3
	v_med3_i32 v8, v8, 0, v230
	v_lshl_add_u32 v8, v8, 2, s57
	ds_read_b32 v8, v8
	v_subrev_u32_e32 v9, 33, v3
	v_med3_i32 v9, v9, 0, v230
	v_lshl_add_u32 v9, v9, 2, s57
	ds_read_b32 v9, v9
	v_subrev_u32_e32 v10, 34, v3
	v_med3_i32 v10, v10, 0, v230
	v_lshl_add_u32 v10, v10, 2, s57
	ds_read_b32 v10, v10
	v_subrev_u32_e32 v11, 35, v3
	v_med3_i32 v11, v11, 0, v230
	v_lshl_add_u32 v11, v11, 2, s57
	ds_read_b32 v11, v11
	v_subrev_u32_e32 v12, 32, v0
	v_med3_i32 v12, v12, 0, v230
	v_lshl_add_u32 v12, v12, 2, s57
	ds_read_b32 v12, v12
	v_subrev_u32_e32 v13, 33, v0
	v_med3_i32 v13, v13, 0, v230
	v_lshl_add_u32 v13, v13, 2, s57
	ds_read_b32 v13, v13
	v_subrev_u32_e32 v14, 34, v0
	v_med3_i32 v14, v14, 0, v230
	v_lshl_add_u32 v14, v14, 2, s57
	ds_read_b32 v14, v14
	v_subrev_u32_e32 v15, 35, v0
	v_med3_i32 v15, v15, 0, v230
	v_lshl_add_u32 v15, v15, 2, s57
	ds_read_b32 v15, v15
	v_cmp_lt_i32_e64 s[4:5], -1, v7
	s_and_b64 s[30:31], vcc, s[4:5]
	v_cmp_gt_u32_e64 s[4:5], s83, v7
	s_or_b64 s[4:5], s[8:9], s[4:5]
	s_waitcnt lgkmcnt(15)
	v_add_f32_e32 v224, v168, v224
	s_and_b64 s[4:5], s[30:31], s[4:5]
	v_cndmask_b32_e64 v168, v231, v224, s[4:5]
	v_subrev_u32_e32 v247, 1, v7
	v_cmp_lt_i32_e64 s[4:5], -1, v247
	s_and_b64 s[30:31], vcc, s[4:5]
	v_cmp_gt_u32_e64 s[4:5], s83, v247
	s_or_b64 s[4:5], s[8:9], s[4:5]
	s_waitcnt lgkmcnt(14)
	v_add_f32_e32 v225, v169, v225
	s_and_b64 s[4:5], s[30:31], s[4:5]
	v_cndmask_b32_e64 v169, v231, v225, s[4:5]
	v_subrev_u32_e32 v246, 2, v7
	v_cmp_lt_i32_e64 s[4:5], -1, v246
	s_and_b64 s[30:31], vcc, s[4:5]
	v_cmp_gt_u32_e64 s[4:5], s83, v246
	s_or_b64 s[4:5], s[8:9], s[4:5]
	s_waitcnt lgkmcnt(13)
	v_add_f32_e32 v226, v170, v226
	s_and_b64 s[4:5], s[30:31], s[4:5]
	v_cndmask_b32_e64 v170, v231, v226, s[4:5]
	v_subrev_u32_e32 v247, 3, v7
	v_cmp_lt_i32_e64 s[4:5], -1, v247
	s_and_b64 s[30:31], vcc, s[4:5]
	v_cmp_gt_u32_e64 s[4:5], s83, v247
	s_or_b64 s[4:5], s[8:9], s[4:5]
	s_waitcnt lgkmcnt(12)
	v_add_f32_e32 v227, v171, v227
	s_and_b64 s[4:5], s[30:31], s[4:5]
	v_cndmask_b32_e64 v171, v231, v227, s[4:5]
	v_cmp_lt_i32_e64 s[4:5], -1, v2
	s_and_b64 s[30:31], vcc, s[4:5]
	v_cmp_gt_u32_e64 s[4:5], s83, v2
	s_or_b64 s[4:5], s[8:9], s[4:5]
	s_waitcnt lgkmcnt(11)
	v_add_f32_e32 v250, v172, v250
	s_and_b64 s[4:5], s[30:31], s[4:5]
	v_cndmask_b32_e64 v172, v231, v250, s[4:5]
	v_subrev_u32_e32 v247, 1, v2
	v_cmp_lt_i32_e64 s[4:5], -1, v247
	s_and_b64 s[30:31], vcc, s[4:5]
	v_cmp_gt_u32_e64 s[4:5], s83, v247
	s_or_b64 s[4:5], s[8:9], s[4:5]
	s_waitcnt lgkmcnt(10)
	v_add_f32_e32 v251, v173, v251
	s_and_b64 s[4:5], s[30:31], s[4:5]
	v_cndmask_b32_e64 v173, v231, v251, s[4:5]
	v_subrev_u32_e32 v246, 2, v2
	v_cmp_lt_i32_e64 s[4:5], -1, v246
	s_and_b64 s[30:31], vcc, s[4:5]
	v_cmp_gt_u32_e64 s[4:5], s83, v246
	s_or_b64 s[4:5], s[8:9], s[4:5]
	s_waitcnt lgkmcnt(9)
	v_add_f32_e32 v252, v174, v252
	s_and_b64 s[4:5], s[30:31], s[4:5]
	v_cndmask_b32_e64 v174, v231, v252, s[4:5]
	v_subrev_u32_e32 v247, 3, v2
	v_cmp_lt_i32_e64 s[4:5], -1, v247
	s_and_b64 s[30:31], vcc, s[4:5]
	v_cmp_gt_u32_e64 s[4:5], s83, v247
	s_or_b64 s[4:5], s[8:9], s[4:5]
	s_waitcnt lgkmcnt(8)
	v_add_f32_e32 v253, v175, v253
	s_and_b64 s[4:5], s[30:31], s[4:5]
	v_cndmask_b32_e64 v175, v231, v253, s[4:5]
	v_subrev_u32_e32 v224, 32, v7
	v_med3_i32 v224, v224, 0, v230
	v_lshl_add_u32 v224, v224, 2, s57
	ds_read_b32 v224, v224
	v_subrev_u32_e32 v225, 33, v7
	v_med3_i32 v225, v225, 0, v230
	v_lshl_add_u32 v225, v225, 2, s57
	ds_read_b32 v225, v225
	v_subrev_u32_e32 v226, 34, v7
	v_med3_i32 v226, v226, 0, v230
	v_lshl_add_u32 v226, v226, 2, s57
	ds_read_b32 v226, v226
	v_subrev_u32_e32 v227, 35, v7
	v_med3_i32 v227, v227, 0, v230
	v_lshl_add_u32 v227, v227, 2, s57
	ds_read_b32 v227, v227
	v_subrev_u32_e32 v250, 32, v2
	v_med3_i32 v250, v250, 0, v230
	v_lshl_add_u32 v250, v250, 2, s57
	ds_read_b32 v250, v250
	v_subrev_u32_e32 v251, 33, v2
	v_med3_i32 v251, v251, 0, v230
	v_lshl_add_u32 v251, v251, 2, s57
	ds_read_b32 v251, v251
	v_subrev_u32_e32 v252, 34, v2
	v_med3_i32 v252, v252, 0, v230
	v_lshl_add_u32 v252, v252, 2, s57
	ds_read_b32 v252, v252
	v_subrev_u32_e32 v253, 35, v2
	v_med3_i32 v253, v253, 0, v230
	v_lshl_add_u32 v253, v253, 2, s57
	ds_read_b32 v253, v253
	v_subrev_u32_e32 v246, 32, v3
	v_cmp_lt_i32_e64 s[4:5], -1, v246
	s_and_b64 s[30:31], vcc, s[4:5]
	v_cmp_gt_u32_e64 s[4:5], s83, v246
	s_or_b64 s[4:5], s[8:9], s[4:5]
	s_waitcnt lgkmcnt(15)
; DI void nsa_attn_phase(int wv, LAS unsigned char* lds, const bf16_t* Q, const bf16_t* slab, const bf16_t* VT2, const float* gates, const bf16_t* KCMP, const bf16_t* VCMPT,
;                        const float* rel_bias, bf16_t* O) {
;     ...
;                     if (!far) {
;                         const int d0 = tq - k0 - 4 * hh;
; #pragma unroll
;                         for (int t = 0; t < 2; ++t)
; #pragma unroll
;                             for (int i = 0; i < 16; ++i) {
;                                 const int dist = d0 - (32 * t + (i & 3) + 8 * (i >> 2));
;                                 const float bias = mylut[dist < 0 ? 0 : (dist > 127 ? 127 : dist)];
;                                 const bool valid = selbit && dist >= 0 && (br == 0 || dist < 512);
;                                 s[t][i] = valid ? s[t][i] + bias : NEGF;
;                             }
	v_add_f32_e32 v8, v144, v8
	s_and_b64 s[4:5], s[30:31], s[4:5]
	v_cndmask_b32_e64 v144, v231, v8, s[4:5]
	v_subrev_u32_e32 v247, 33, v3
	v_cmp_lt_i32_e64 s[4:5], -1, v247
	s_and_b64 s[30:31], vcc, s[4:5]
	v_cmp_gt_u32_e64 s[4:5], s83, v247
	s_or_b64 s[4:5], s[8:9], s[4:5]
	s_waitcnt lgkmcnt(14)
	v_add_f32_e32 v9, v145, v9
	s_and_b64 s[4:5], s[30:31], s[4:5]
	v_cndmask_b32_e64 v145, v231, v9, s[4:5]
	v_subrev_u32_e32 v246, 34, v3
	v_cmp_lt_i32_e64 s[4:5], -1, v246
	s_and_b64 s[30:31], vcc, s[4:5]
	v_cmp_gt_u32_e64 s[4:5], s83, v246
	s_or_b64 s[4:5], s[8:9], s[4:5]
	s_waitcnt lgkmcnt(13)
	v_add_f32_e32 v10, v146, v10
	s_and_b64 s[4:5], s[30:31], s[4:5]
	v_cndmask_b32_e64 v146, v231, v10, s[4:5]
	v_subrev_u32_e32 v247, 35, v3
	v_cmp_lt_i32_e64 s[4:5], -1, v247
	s_and_b64 s[30:31], vcc, s[4:5]
	v_cmp_gt_u32_e64 s[4:5], s83, v247
	s_or_b64 s[4:5], s[8:9], s[4:5]
	s_waitcnt lgkmcnt(12)
	v_add_f32_e32 v11, v147, v11
	s_and_b64 s[4:5], s[30:31], s[4:5]
	v_cndmask_b32_e64 v147, v231, v11, s[4:5]
	v_subrev_u32_e32 v246, 32, v0
	v_cmp_lt_i32_e64 s[4:5], -1, v246
	s_and_b64 s[30:31], vcc, s[4:5]
	v_cmp_gt_u32_e64 s[4:5], s83, v246
	s_or_b64 s[4:5], s[8:9], s[4:5]
	s_waitcnt lgkmcnt(11)
	v_add_f32_e32 v12, v148, v12
	s_and_b64 s[4:5], s[30:31], s[4:5]
	v_cndmask_b32_e64 v148, v231, v12, s[4:5]
	v_subrev_u32_e32 v247, 33, v0
	v_cmp_lt_i32_e64 s[4:5], -1, v247
	s_and_b64 s[30:31], vcc, s[4:5]
	v_cmp_gt_u32_e64 s[4:5], s83, v247
	s_or_b64 s[4:5], s[8:9], s[4:5]
	s_waitcnt lgkmcnt(10)
	v_add_f32_e32 v13, v149, v13
	s_and_b64 s[4:5], s[30:31], s[4:5]
	v_cndmask_b32_e64 v149, v231, v13, s[4:5]
	v_subrev_u32_e32 v246, 34, v0
	v_cmp_lt_i32_e64 s[4:5], -1, v246
	s_and_b64 s[30:31], vcc, s[4:5]
	v_cmp_gt_u32_e64 s[4:5], s83, v246
	s_or_b64 s[4:5], s[8:9], s[4:5]
	s_waitcnt lgkmcnt(9)
	v_add_f32_e32 v14, v150, v14
	s_and_b64 s[4:5], s[30:31], s[4:5]
	v_cndmask_b32_e64 v150, v231, v14, s[4:5]
	v_subrev_u32_e32 v247, 35, v0
	v_cmp_lt_i32_e64 s[4:5], -1, v247
	s_and_b64 s[30:31], vcc, s[4:5]
	v_cmp_gt_u32_e64 s[4:5], s83, v247
	s_or_b64 s[4:5], s[8:9], s[4:5]
	s_waitcnt lgkmcnt(8)
	v_add_f32_e32 v15, v151, v15
	s_and_b64 s[4:5], s[30:31], s[4:5]
	v_cndmask_b32_e64 v151, v231, v15, s[4:5]
	v_subrev_u32_e32 v246, 32, v7
	v_cmp_lt_i32_e64 s[4:5], -1, v246
	s_and_b64 s[30:31], vcc, s[4:5]
	v_cmp_gt_u32_e64 s[4:5], s83, v246
	s_or_b64 s[4:5], s[8:9], s[4:5]
	s_waitcnt lgkmcnt(7)
	v_add_f32_e32 v224, v152, v224
	s_and_b64 s[4:5], s[30:31], s[4:5]
	v_cndmask_b32_e64 v152, v231, v224, s[4:5]
	v_subrev_u32_e32 v247, 33, v7
	v_cmp_lt_i32_e64 s[4:5], -1, v247
	s_and_b64 s[30:31], vcc, s[4:5]
	v_cmp_gt_u32_e64 s[4:5], s83, v247
	s_or_b64 s[4:5], s[8:9], s[4:5]
	s_waitcnt lgkmcnt(6)
	v_add_f32_e32 v225, v153, v225
	s_and_b64 s[4:5], s[30:31], s[4:5]
	v_cndmask_b32_e64 v153, v231, v225, s[4:5]
	v_subrev_u32_e32 v246, 34, v7
	v_cmp_lt_i32_e64 s[4:5], -1, v246
	s_and_b64 s[30:31], vcc, s[4:5]
	v_cmp_gt_u32_e64 s[4:5], s83, v246
	s_or_b64 s[4:5], s[8:9], s[4:5]
	s_waitcnt lgkmcnt(5)
	v_add_f32_e32 v226, v154, v226
	s_and_b64 s[4:5], s[30:31], s[4:5]
	v_cndmask_b32_e64 v154, v231, v226, s[4:5]
	v_subrev_u32_e32 v247, 35, v7
	v_cmp_lt_i32_e64 s[4:5], -1, v247
	s_and_b64 s[30:31], vcc, s[4:5]
	v_cmp_gt_u32_e64 s[4:5], s83, v247
	s_or_b64 s[4:5], s[8:9], s[4:5]
	s_waitcnt lgkmcnt(4)
	v_add_f32_e32 v227, v155, v227
	s_and_b64 s[4:5], s[30:31], s[4:5]
	v_cndmask_b32_e64 v155, v231, v227, s[4:5]
	v_subrev_u32_e32 v246, 32, v2
	v_cmp_lt_i32_e64 s[4:5], -1, v246
	s_and_b64 s[30:31], vcc, s[4:5]
	v_cmp_gt_u32_e64 s[4:5], s83, v246
	s_or_b64 s[4:5], s[8:9], s[4:5]
	s_waitcnt lgkmcnt(3)
	v_add_f32_e32 v250, v156, v250
	s_and_b64 s[4:5], s[30:31], s[4:5]
	v_cndmask_b32_e64 v156, v231, v250, s[4:5]
	v_subrev_u32_e32 v247, 33, v2
	v_cmp_lt_i32_e64 s[4:5], -1, v247
	s_and_b64 s[30:31], vcc, s[4:5]
	v_cmp_gt_u32_e64 s[4:5], s83, v247
	s_or_b64 s[4:5], s[8:9], s[4:5]
	s_waitcnt lgkmcnt(2)
	v_add_f32_e32 v251, v157, v251
	s_and_b64 s[4:5], s[30:31], s[4:5]
	v_cndmask_b32_e64 v157, v231, v251, s[4:5]
	v_subrev_u32_e32 v246, 34, v2
	v_cmp_lt_i32_e64 s[4:5], -1, v246
	s_and_b64 s[30:31], vcc, s[4:5]
	v_cmp_gt_u32_e64 s[4:5], s83, v246
	s_or_b64 s[4:5], s[8:9], s[4:5]
	s_waitcnt lgkmcnt(1)
	v_add_f32_e32 v252, v158, v252
	s_and_b64 s[4:5], s[30:31], s[4:5]
	v_cndmask_b32_e64 v158, v231, v252, s[4:5]
	v_subrev_u32_e32 v247, 35, v2
	v_cmp_lt_i32_e64 s[4:5], -1, v247
	s_and_b64 s[30:31], vcc, s[4:5]
	v_cmp_gt_u32_e64 s[4:5], s83, v247
	s_or_b64 s[4:5], s[8:9], s[4:5]
	s_waitcnt lgkmcnt(0)
	v_add_f32_e32 v253, v159, v253
	s_and_b64 s[4:5], s[30:31], s[4:5]
	v_cndmask_b32_e64 v159, v231, v253, s[4:5]
